# v_f1 + attention wave-role permutation: the younger half (waves 4-7) owns query groups 0,1, so each unit's diagonal tile runs one wave per SIMD on the older half
# baseline (speedup 1.0000x reference)
.LBB0_986:
	s_lshl_b32 s0, s60, 1
	s_and_b32 s36, s0, 0x300
	s_ashr_i32 s0, s81, 4
	v_readfirstlane_b32 s22, v184
	s_bfe_u32 s32, s22, 0x10007
	s_bfe_u32 s89, s22, 0x10008
	s_xor_b32 s89, s89, 1
	s_and_b32 s22, s22, 0x7f
	s_lshl_b32 s32, s32, 8
	s_lshl_b32 s89, s89, 7
	s_or_b32 s22, s22, s32
	s_or_b32 s22, s22, s89
	s_bfe_u32 s30, s22, 0x20006
	s_ashr_i32 s1, s0, 31
	s_lshl_b64 s[10:11], s[0:1], 11
	s_lshl_b32 s33, s30, 5
	s_or_b32 s1, s10, s33
	s_mul_i32 s6, s11, 0x1600
	s_mul_hi_u32 s7, s1, 0x1600
	s_and_b32 s62, s81, 3
	s_lshr_b32 s14, s22, 6
	s_lshr_b32 s15, s22, 8
	s_add_i32 s7, s7, s6
	s_mulk_i32 s1, 0x1600
	s_add_u32 s1, s66, s1
	s_addc_u32 s6, s67, s7
	s_lshl_b32 s7, s81, 6
	s_and_b32 s18, s7, 0x300
	s_add_u32 s1, s1, s18
	s_addc_u32 s6, s6, 0
	s_lshl_b32 s7, s15, 7
	s_add_u32 s12, s1, s7
	s_addc_u32 s13, s6, 0
	s_mul_i32 s38, s0, 0xb00000
	s_mul_hi_i32 s37, s0, 0xb00000
	s_add_u32 s0, s4, s38
	s_addc_u32 s1, s5, s37
	s_add_u32 s34, s0, s18
	s_addc_u32 s35, s1, 0
	s_add_u32 s0, s52, s38
	s_addc_u32 s1, s53, s37
	s_add_u32 s6, s0, s18
	v_lshl_or_b32 v0, s14, 3, v164
	s_movk_i32 s0, 0x1600
	s_addc_u32 s7, s1, 0
	v_mul_lo_u32 v0, v0, s0
	s_lshr_b32 s0, s22, 4
	s_and_b32 s0, s0, 4
	v_bitop3_b32 v1, s0, v165, v166 bitop3:0x36
	s_lshl_b32 s0, s15, 5
	v_lshl_or_b32 v211, v1, 4, v0
	v_lshl_or_b32 v0, s30, 4, v167
	v_mov_b32_e32 v1, s0
	s_movk_i32 s0, 0xb00
	v_mad_u32_u24 v0, v0, s0, v1
	s_lshl_b32 s0, s14, 10
	v_or_b32_e32 v0, v0, v168
	s_add_i32 s63, s0, 0x100
	v_lshlrev_b32_e32 v212, 1, v0
	s_add_i32 s0, s63, 0x18000
	v_lshl_or_b32 v0, s62, 7, v163
	s_waitcnt lgkmcnt(0)
	s_barrier
	s_mov_b32 s1, m0
	s_mov_b32 m0, s0
	s_nop 0
	global_load_lds_dwordx4 v211, s[34:35]
	s_mov_b32 m0, s1
	s_add_u32 s0, s34, 0x80
	v_mul_u32_u24_e32 v0, 0xb00, v0
	s_addc_u32 s1, s35, 0
	s_add_i32 s16, s63, 0x1a000
	s_mov_b32 s17, m0
	s_mov_b32 m0, s16
	s_nop 0
	global_load_lds_dwordx4 v211, s[0:1]
	s_mov_b32 m0, s17
	s_add_i32 s0, s63, 0x1c000
	v_lshlrev_b32_e32 v156, 1, v0
	s_mov_b32 s1, m0
	s_mov_b32 m0, s0
	s_nop 0
	global_load_lds_dwordx4 v212, s[6:7]
	s_mov_b32 m0, s1
	s_add_u32 s0, s6, 0x80
	v_lshl_add_u64 v[0:1], s[12:13], 0, v[156:157]
	s_addc_u32 s1, s7, 0
	s_add_i32 s16, s63, 0x1e000
	s_mov_b32 s17, m0
	s_mov_b32 m0, s16
	s_nop 0
	global_load_lds_dwordx4 v212, s[0:1]
	s_mov_b32 m0, s17
	v_lshl_add_u64 v[0:1], v[0:1], 0, v[158:159]
	global_load_dwordx4 v[112:115], v[0:1], off
	global_load_dwordx4 v[116:119], v[0:1], off offset:32
	global_load_dwordx4 v[120:123], v[0:1], off offset:64
	global_load_dwordx4 v[124:127], v[0:1], off offset:96
	s_add_i32 s68, s63, 0x4000
	s_bfe_u32 s69, s14, 0x10001
	s_add_u32 s14, s34, 0x58000
	v_lshl_add_u32 v213, s15, 13, v169
	s_addc_u32 s15, s35, 0
	s_add_u32 s16, s6, 0x58000
	s_addc_u32 s17, s7, 0
	s_add_u32 s70, s74, s18
	s_addc_u32 s71, s75, 0
	s_xor_b32 s72, s62, 7
	s_or_b32 s73, s62, 8
	s_xor_b32 s76, s62, 15
	s_add_u32 s18, s34, 0x58080
	s_addc_u32 s19, s35, 0
	s_add_u32 s20, s6, 0x58080
	s_addc_u32 s21, s7, 0
	s_cmpk_gt_u32 s22, 0xff
	s_cselect_b64 s[0:1], -1, 0
	s_lshl_b32 s22, s30, 14
	s_add_i32 s77, s22, 0x100
	s_lshl_b32 s22, s30, 13
	s_add_i32 s78, s22, 0x100
	s_add_i32 s78, s78, 0x10000
	s_add_i32 s79, s69, 1
	s_add_u32 s22, s34, 0xb0000
	s_addc_u32 s23, s35, 0
	s_add_u32 s24, s34, 0xb0080
	s_addc_u32 s25, s35, 0
	s_add_u32 s26, s6, 0xb0000
	s_addc_u32 s27, s7, 0
	s_add_u32 s28, s6, 0xb0080
	s_addc_u32 s29, s7, 0
	s_cmp_lt_u32 s30, 2
	s_cselect_b64 s[30:31], -1, 0
	s_add_u32 s34, s34, 0x108000
	s_addc_u32 s35, s35, 0
	s_or_b32 s36, s38, s36
	s_add_u32 s36, s54, s36
	s_addc_u32 s37, s55, s37
	s_add_u32 s38, s6, 0x108000
	v_cndmask_b32_e64 v214, 1.0, v160, s[0:1]
	v_add_u32_e32 v215, 0x18000, v213
	s_addc_u32 s39, s7, 0
	s_mov_b32 s80, 0
	s_waitcnt vmcnt(0)
	s_branch .LBB0_989
